# v28: v27 + barriers 2..6 issue census loads and arrival atomic together
# speedup vs baseline: 1.0077x; 1.0009x over previous
.LBB0_285:
	s_or_b64 exec, exec, s[10:11]
	s_waitcnt vmcnt(0)
	s_cmp_eq_u32 s0, 0
	s_cselect_b64 vcc, -1, 0
	s_cmp_eq_u32 s0, 1
	v_cndmask_b32_e32 v18, 1, v15, vcc
	s_cselect_b64 vcc, -1, 0
	s_cmp_eq_u32 s0, 2
	v_cndmask_b32_e32 v18, v18, v0, vcc
	s_cselect_b64 vcc, -1, 0
	s_cmp_eq_u32 s0, 3
	v_cndmask_b32_e32 v18, v18, v1, vcc
	s_cselect_b64 vcc, -1, 0
	s_cmp_eq_u32 s0, 4
	v_cndmask_b32_e32 v18, v18, v2, vcc
	s_cselect_b64 vcc, -1, 0
	s_cmp_eq_u32 s0, 5
	v_cndmask_b32_e32 v18, v18, v3, vcc
	s_cselect_b64 vcc, -1, 0
	s_cmp_eq_u32 s0, 6
	v_cndmask_b32_e32 v18, v18, v4, vcc
	s_cselect_b64 vcc, -1, 0
	s_cmp_eq_u32 s0, 7
	v_cndmask_b32_e32 v18, v18, v5, vcc
	s_cselect_b64 vcc, -1, 0
	s_cmp_eq_u32 s0, 8
	v_cndmask_b32_e32 v18, v18, v6, vcc
	s_cselect_b64 vcc, -1, 0
	s_cmp_eq_u32 s0, 9
	v_cndmask_b32_e32 v18, v18, v7, vcc
	s_cselect_b64 vcc, -1, 0
	s_cmp_eq_u32 s0, 10
	v_cndmask_b32_e32 v18, v18, v8, vcc
	s_cselect_b64 vcc, -1, 0
	s_cmp_eq_u32 s0, 11
	v_cndmask_b32_e32 v18, v18, v9, vcc
	s_cselect_b64 vcc, -1, 0
	s_cmp_eq_u32 s0, 12
	v_cndmask_b32_e32 v18, v18, v10, vcc
	s_cselect_b64 vcc, -1, 0
	s_cmp_eq_u32 s0, 13
	v_cndmask_b32_e32 v18, v18, v11, vcc
	s_cselect_b64 vcc, -1, 0
	s_cmp_eq_u32 s0, 14
	v_cndmask_b32_e32 v18, v18, v12, vcc
	s_cselect_b64 vcc, -1, 0
	s_cmp_eq_u32 s0, 15
	v_cndmask_b32_e32 v18, v18, v13, vcc
	s_cselect_b64 vcc, -1, 0
	v_cndmask_b32_e32 v18, v18, v14, vcc
	v_cvt_f32_u32_e32 v19, v18
	s_waitcnt vmcnt(0)
	v_readfirstlane_b32 s0, v17
	v_rcp_iflag_f32_e32 v19, v19
	s_nop 0
	v_add_u32_e32 v17, s0, v16
	v_sub_u32_e32 v16, 0, v18
	v_mul_f32_e32 v19, 0x4f7ffffe, v19
	v_cvt_u32_f32_e32 v19, v19
	v_mul_lo_u32 v16, v16, v19
	v_mul_hi_u32 v16, v19, v16
	v_add_u32_e32 v16, v19, v16
	v_mul_hi_u32 v16, v17, v16
	v_mul_lo_u32 v19, v16, v18
	v_sub_u32_e32 v19, v17, v19
	v_add_u32_e32 v20, 1, v16
	v_cmp_ge_u32_e32 vcc, v19, v18
	v_add_u32_e32 v17, 1, v17
	s_nop 0
	v_cndmask_b32_e32 v16, v16, v20, vcc
	v_sub_u32_e32 v20, v19, v18
	v_cndmask_b32_e32 v19, v19, v20, vcc
	v_add_u32_e32 v20, 1, v16
	v_cmp_ge_u32_e32 vcc, v19, v18
	s_nop 1
	v_cndmask_b32_e32 v16, v16, v20, vcc
	v_mul_lo_u32 v19, v18, v16
	v_add_u32_e32 v18, v19, v18
	v_cmp_ne_u32_e32 vcc, v17, v18
	s_and_saveexec_b64 s[0:1], vcc
	s_xor_b64 s[8:9], exec, s[0:1]
	s_cbranch_execz .LBB0_290
	s_add_u32 s10, s70, 0x3500
	s_addc_u32 s11, s71, 0
	v_mov_b32_e32 v17, 0
	global_load_dword v17, v17, s[10:11] sc1
	s_waitcnt vmcnt(0)
	v_cmp_eq_u32_e32 vcc, v17, v16
	s_and_saveexec_b64 s[28:29], vcc
	s_cbranch_execz .LBB0_289
	s_mov_b64 s[30:31], 0
	v_mov_b32_e32 v17, 0

.LBB0_569:
	s_or_b64 exec, exec, s[10:11]
	s_waitcnt vmcnt(0)
	s_cmp_eq_u32 s0, 0
	s_cselect_b64 vcc, -1, 0
	s_cmp_eq_u32 s0, 1
	v_cndmask_b32_e32 v18, 1, v15, vcc
	s_cselect_b64 vcc, -1, 0
	s_cmp_eq_u32 s0, 2
	v_cndmask_b32_e32 v18, v18, v0, vcc
	s_cselect_b64 vcc, -1, 0
	s_cmp_eq_u32 s0, 3
	v_cndmask_b32_e32 v18, v18, v1, vcc
	s_cselect_b64 vcc, -1, 0
	s_cmp_eq_u32 s0, 4
	v_cndmask_b32_e32 v18, v18, v2, vcc
	s_cselect_b64 vcc, -1, 0
	s_cmp_eq_u32 s0, 5
	v_cndmask_b32_e32 v18, v18, v3, vcc
	s_cselect_b64 vcc, -1, 0
	s_cmp_eq_u32 s0, 6
	v_cndmask_b32_e32 v18, v18, v4, vcc
	s_cselect_b64 vcc, -1, 0
	s_cmp_eq_u32 s0, 7
	v_cndmask_b32_e32 v18, v18, v5, vcc
	s_cselect_b64 vcc, -1, 0
	s_cmp_eq_u32 s0, 8
	v_cndmask_b32_e32 v18, v18, v6, vcc
	s_cselect_b64 vcc, -1, 0
	s_cmp_eq_u32 s0, 9
	v_cndmask_b32_e32 v18, v18, v7, vcc
	s_cselect_b64 vcc, -1, 0
	s_cmp_eq_u32 s0, 10
	v_cndmask_b32_e32 v18, v18, v8, vcc
	s_cselect_b64 vcc, -1, 0
	s_cmp_eq_u32 s0, 11
	v_cndmask_b32_e32 v18, v18, v9, vcc
	s_cselect_b64 vcc, -1, 0
	s_cmp_eq_u32 s0, 12
	v_cndmask_b32_e32 v18, v18, v10, vcc
	s_cselect_b64 vcc, -1, 0
	s_cmp_eq_u32 s0, 13
	v_cndmask_b32_e32 v18, v18, v11, vcc
	s_cselect_b64 vcc, -1, 0
	s_cmp_eq_u32 s0, 14
	v_cndmask_b32_e32 v18, v18, v12, vcc
	s_cselect_b64 vcc, -1, 0
	s_cmp_eq_u32 s0, 15
	v_cndmask_b32_e32 v18, v18, v13, vcc
	s_cselect_b64 vcc, -1, 0
	v_cndmask_b32_e32 v18, v18, v14, vcc
	v_cvt_f32_u32_e32 v19, v18
	s_waitcnt vmcnt(0)
	v_readfirstlane_b32 s0, v17
	v_rcp_iflag_f32_e32 v19, v19
	s_nop 0
	v_add_u32_e32 v17, s0, v16
	v_sub_u32_e32 v16, 0, v18
	v_mul_f32_e32 v19, 0x4f7ffffe, v19
	v_cvt_u32_f32_e32 v19, v19
	v_mul_lo_u32 v16, v16, v19
	v_mul_hi_u32 v16, v19, v16
	v_add_u32_e32 v16, v19, v16
	v_mul_hi_u32 v16, v17, v16
	v_mul_lo_u32 v19, v16, v18
	v_sub_u32_e32 v19, v17, v19
	v_add_u32_e32 v20, 1, v16
	v_cmp_ge_u32_e32 vcc, v19, v18
	v_add_u32_e32 v17, 1, v17
	s_nop 0
	v_cndmask_b32_e32 v16, v16, v20, vcc
	v_sub_u32_e32 v20, v19, v18
	v_cndmask_b32_e32 v19, v19, v20, vcc
	v_add_u32_e32 v20, 1, v16
	v_cmp_ge_u32_e32 vcc, v19, v18
	s_nop 1
	v_cndmask_b32_e32 v16, v16, v20, vcc
	v_mul_lo_u32 v19, v18, v16
	v_add_u32_e32 v18, v19, v18
	v_cmp_ne_u32_e32 vcc, v17, v18
	s_and_saveexec_b64 s[0:1], vcc
	s_xor_b64 s[8:9], exec, s[0:1]
	s_cbranch_execz .LBB0_574
	s_add_u32 s10, s70, 0x3500
	s_addc_u32 s11, s71, 0
	v_mov_b32_e32 v17, 0
	global_load_dword v17, v17, s[10:11] sc1
	s_waitcnt vmcnt(0)
	v_cmp_eq_u32_e32 vcc, v17, v16
	s_and_saveexec_b64 s[12:13], vcc
	s_cbranch_execz .LBB0_573
	s_mov_b64 s[14:15], 0
	v_mov_b32_e32 v17, 0

.LBB0_1403:
	s_or_b64 exec, exec, s[12:13]
	s_waitcnt vmcnt(0)
	s_cmp_eq_u32 s0, 0
	s_cselect_b64 vcc, -1, 0
	s_cmp_eq_u32 s0, 1
	v_cndmask_b32_e32 v18, 1, v15, vcc
	s_cselect_b64 vcc, -1, 0
	s_cmp_eq_u32 s0, 2
	v_cndmask_b32_e32 v18, v18, v0, vcc
	s_cselect_b64 vcc, -1, 0
	s_cmp_eq_u32 s0, 3
	v_cndmask_b32_e32 v18, v18, v1, vcc
	s_cselect_b64 vcc, -1, 0
	s_cmp_eq_u32 s0, 4
	v_cndmask_b32_e32 v18, v18, v2, vcc
	s_cselect_b64 vcc, -1, 0
	s_cmp_eq_u32 s0, 5
	v_cndmask_b32_e32 v18, v18, v3, vcc
	s_cselect_b64 vcc, -1, 0
	s_cmp_eq_u32 s0, 6
	v_cndmask_b32_e32 v18, v18, v4, vcc
	s_cselect_b64 vcc, -1, 0
	s_cmp_eq_u32 s0, 7
	v_cndmask_b32_e32 v18, v18, v5, vcc
	s_cselect_b64 vcc, -1, 0
	s_cmp_eq_u32 s0, 8
	v_cndmask_b32_e32 v18, v18, v6, vcc
	s_cselect_b64 vcc, -1, 0
	s_cmp_eq_u32 s0, 9
	v_cndmask_b32_e32 v18, v18, v7, vcc
	s_cselect_b64 vcc, -1, 0
	s_cmp_eq_u32 s0, 10
	v_cndmask_b32_e32 v18, v18, v8, vcc
	s_cselect_b64 vcc, -1, 0
	s_cmp_eq_u32 s0, 11
	v_cndmask_b32_e32 v18, v18, v9, vcc
	s_cselect_b64 vcc, -1, 0
	s_cmp_eq_u32 s0, 12
	v_cndmask_b32_e32 v18, v18, v10, vcc
	s_cselect_b64 vcc, -1, 0
	s_cmp_eq_u32 s0, 13
	v_cndmask_b32_e32 v18, v18, v11, vcc
	s_cselect_b64 vcc, -1, 0
	s_cmp_eq_u32 s0, 14
	v_cndmask_b32_e32 v18, v18, v12, vcc
	s_cselect_b64 vcc, -1, 0
	s_cmp_eq_u32 s0, 15
	v_cndmask_b32_e32 v18, v18, v13, vcc
	s_cselect_b64 vcc, -1, 0
	v_cndmask_b32_e32 v18, v18, v14, vcc
	v_cvt_f32_u32_e32 v19, v18
	s_waitcnt vmcnt(0)
	v_readfirstlane_b32 s0, v17
	v_rcp_iflag_f32_e32 v19, v19
	s_nop 0
	v_add_u32_e32 v17, s0, v16
	v_sub_u32_e32 v16, 0, v18
	v_mul_f32_e32 v19, 0x4f7ffffe, v19
	v_cvt_u32_f32_e32 v19, v19
	v_mul_lo_u32 v16, v16, v19
	v_mul_hi_u32 v16, v19, v16
	v_add_u32_e32 v16, v19, v16
	v_mul_hi_u32 v16, v17, v16
	v_mul_lo_u32 v19, v16, v18
	v_sub_u32_e32 v19, v17, v19
	v_add_u32_e32 v20, 1, v16
	v_cmp_ge_u32_e32 vcc, v19, v18
	v_add_u32_e32 v17, 1, v17
	s_nop 0
	v_cndmask_b32_e32 v16, v16, v20, vcc
	v_sub_u32_e32 v20, v19, v18
	v_cndmask_b32_e32 v19, v19, v20, vcc
	v_add_u32_e32 v20, 1, v16
	v_cmp_ge_u32_e32 vcc, v19, v18
	s_nop 1
	v_cndmask_b32_e32 v16, v16, v20, vcc
	v_mul_lo_u32 v19, v18, v16
	v_add_u32_e32 v18, v19, v18
	v_cmp_ne_u32_e32 vcc, v17, v18
	s_and_saveexec_b64 s[0:1], vcc
	s_xor_b64 s[10:11], exec, s[0:1]
	s_cbranch_execz .LBB0_1408
	s_add_u32 s12, s70, 0x3500
	s_addc_u32 s13, s71, 0
	v_mov_b32_e32 v17, 0
	global_load_dword v17, v17, s[12:13] sc1
	s_waitcnt vmcnt(0)
	v_cmp_eq_u32_e32 vcc, v17, v16
	s_and_saveexec_b64 s[14:15], vcc
	s_cbranch_execz .LBB0_1407
	s_mov_b64 s[16:17], 0
	v_mov_b32_e32 v17, 0

.LBB0_1463:
	s_or_b64 exec, exec, s[8:9]
	s_waitcnt vmcnt(0)
	s_cmp_eq_u32 s5, 0
	s_cselect_b64 vcc, -1, 0
	s_cmp_eq_u32 s5, 1
	v_cndmask_b32_e32 v18, 1, v15, vcc
	s_cselect_b64 vcc, -1, 0
	s_cmp_eq_u32 s5, 2
	v_cndmask_b32_e32 v18, v18, v0, vcc
	s_cselect_b64 vcc, -1, 0
	s_cmp_eq_u32 s5, 3
	v_cndmask_b32_e32 v18, v18, v1, vcc
	s_cselect_b64 vcc, -1, 0
	s_cmp_eq_u32 s5, 4
	v_cndmask_b32_e32 v18, v18, v2, vcc
	s_cselect_b64 vcc, -1, 0
	s_cmp_eq_u32 s5, 5
	v_cndmask_b32_e32 v18, v18, v3, vcc
	s_cselect_b64 vcc, -1, 0
	s_cmp_eq_u32 s5, 6
	v_cndmask_b32_e32 v18, v18, v4, vcc
	s_cselect_b64 vcc, -1, 0
	s_cmp_eq_u32 s5, 7
	v_cndmask_b32_e32 v18, v18, v5, vcc
	s_cselect_b64 vcc, -1, 0
	s_cmp_eq_u32 s5, 8
	v_cndmask_b32_e32 v18, v18, v6, vcc
	s_cselect_b64 vcc, -1, 0
	s_cmp_eq_u32 s5, 9
	v_cndmask_b32_e32 v18, v18, v7, vcc
	s_cselect_b64 vcc, -1, 0
	s_cmp_eq_u32 s5, 10
	v_cndmask_b32_e32 v18, v18, v8, vcc
	s_cselect_b64 vcc, -1, 0
	s_cmp_eq_u32 s5, 11
	v_cndmask_b32_e32 v18, v18, v9, vcc
	s_cselect_b64 vcc, -1, 0
	s_cmp_eq_u32 s5, 12
	v_cndmask_b32_e32 v18, v18, v10, vcc
	s_cselect_b64 vcc, -1, 0
	s_cmp_eq_u32 s5, 13
	v_cndmask_b32_e32 v18, v18, v11, vcc
	s_cselect_b64 vcc, -1, 0
	s_cmp_eq_u32 s5, 14
	v_cndmask_b32_e32 v18, v18, v12, vcc
	s_cselect_b64 vcc, -1, 0
	s_cmp_eq_u32 s5, 15
	v_cndmask_b32_e32 v18, v18, v13, vcc
	s_cselect_b64 vcc, -1, 0
	v_cndmask_b32_e32 v18, v18, v14, vcc
	v_cvt_f32_u32_e32 v19, v18
	s_waitcnt vmcnt(0)
	v_readfirstlane_b32 s5, v17
	v_rcp_iflag_f32_e32 v19, v19
	s_nop 0
	v_add_u32_e32 v17, s5, v16
	v_sub_u32_e32 v16, 0, v18
	v_mul_f32_e32 v19, 0x4f7ffffe, v19
	v_cvt_u32_f32_e32 v19, v19
	v_mul_lo_u32 v16, v16, v19
	v_mul_hi_u32 v16, v19, v16
	v_add_u32_e32 v16, v19, v16
	v_mul_hi_u32 v16, v17, v16
	v_mul_lo_u32 v19, v16, v18
	v_sub_u32_e32 v19, v17, v19
	v_add_u32_e32 v20, 1, v16
	v_cmp_ge_u32_e32 vcc, v19, v18
	v_add_u32_e32 v17, 1, v17
	s_nop 0
	v_cndmask_b32_e32 v16, v16, v20, vcc
	v_sub_u32_e32 v20, v19, v18
	v_cndmask_b32_e32 v19, v19, v20, vcc
	v_add_u32_e32 v20, 1, v16
	v_cmp_ge_u32_e32 vcc, v19, v18
	s_nop 1
	v_cndmask_b32_e32 v16, v16, v20, vcc
	v_mul_lo_u32 v19, v18, v16
	v_add_u32_e32 v18, v19, v18
	v_cmp_ne_u32_e32 vcc, v17, v18
	s_and_saveexec_b64 s[6:7], vcc
	s_xor_b64 s[6:7], exec, s[6:7]
	s_cbranch_execz .LBB0_1468
	s_add_u32 s8, s70, 0x3500
	s_addc_u32 s9, s71, 0
	v_mov_b32_e32 v17, 0
	global_load_dword v17, v17, s[8:9] sc1
	s_waitcnt vmcnt(0)
	v_cmp_eq_u32_e32 vcc, v17, v16
	s_and_saveexec_b64 s[10:11], vcc
	s_cbranch_execz .LBB0_1467
	s_mov_b64 s[12:13], 0
	v_mov_b32_e32 v17, 0
